# last phase prompt rows rewritten by hand: 8 rows per wave straight-line with the loads of six rows in flight
# speedup vs baseline: 1.0031x; 1.0016x over previous
; __device__ __forceinline__ int fresh_tid(int wv) { int l; asm volatile("v_mbcnt_lo_u32_b32 %0, -1, 0\n\tv_mbcnt_hi_u32_b32 %0, -1, %0" : "=v"(l)); return wv * 64 + l; }
; #define LAS __attribute__((address_space(3)))
; __device__ __forceinline__ void rows_load(PR P, const int mode, const int row, const int lane, RowRaw& R) {
;     ...
;     else { const bf16_t* xb = (mode == 2 ? (const bf16_t*)P.out : (const bf16_t*)(P.ws + WS_FO + 34603008)) + (size_t)row * 1024;
; #pragma unroll
;         for (int q = 0; q < 4; ++q) R.xb[q] = __builtin_nontemporal_load((const u32x2*)(xb + (q * 64 + lane) * 4)); }
;     if (mode != 0) { const bf16_t* FO = (const bf16_t*)(P.ws + WS_FO) + (size_t)row * 1024;
; #pragma unroll
;         for (int q = 0; q < 4; ++q) R.fb[q] = __builtin_nontemporal_load((const u32x2*)(FO + (q * 64 + lane) * 4)); }
; __device__ __forceinline__ void rows_phase(PR P, const int mode, LAS float* ldsf, const int wv) {
;     const int tid = fresh_tid(wv); const int lane = tid & 63; const int gw = blockIdx.x * 8 + (tid >> 6), nw = gridDim.x * 8;
;     const float* gpost = P.norm_g + (mode == 1 ? 1 : (mode == 2 ? 3 : 5)) * 1024;
;     const float* gnext = P.norm_g + (mode == 0 ? 0 : (mode == 1 ? 2 : 4)) * 1024;
;     float4 gp[4], gn[4];
; #pragma unroll
;     for (int q = 0; q < 4; ++q) { gp[q] = *(const float4*)(gpost + (q * 64 + lane) * 4); gn[q] = *(const float4*)(gnext + (q * 64 + lane) * 4); }
;     if (gw < MP) {
;         const int last = gw + ((MP - 1 - gw) / nw) * nw;
;         RowRaw R, N;
;         rows_load(P, mode, gw, lane, R);
;         for (int row = gw; row < MP; row += nw) {
;             const int nrow = row + nw < MP ? row + nw : last;
;             rows_load(P, mode, nrow, lane, N);
.LBB0_1135:
	s_or_b64 exec, exec, s[0:1]
	s_waitcnt lgkmcnt(0)
	s_barrier
	v_mbcnt_lo_u32_b32 v0, -1, 0
	v_mbcnt_hi_u32_b32 v0, -1, v0
	s_load_dwordx2 s[0:1], s[38:39], 0x28
	v_add_u32_e32 v17, s33, v0
	v_and_b32_e32 v43, 63, v0
	v_ashrrev_i32_e32 v42, 6, v17
	v_lshlrev_b32_e32 v44, 2, v43
	s_waitcnt lgkmcnt(0)
	s_add_u32 s4, s0, 0x5000
	v_add_u32_e32 v18, s73, v42
	s_movk_i32 s8, 0x4000
	s_addc_u32 s5, s1, 0
	v_mov_b32_e32 v23, 0
	v_cmp_gt_i32_e32 vcc, s8, v18
	v_lshlrev_b32_e32 v16, 2, v44
	s_and_saveexec_b64 s[0:1], vcc
	s_xor_b64 s[6:7], exec, s[0:1]
	s_cbranch_execz .LBB0_1139
	global_load_dwordx4 v[0:3], v16, s[4:5]
	global_load_dwordx4 v[4:7], v16, s[4:5] offset:1024
	global_load_dwordx4 v[8:11], v16, s[4:5] offset:2048
	global_load_dwordx4 v[12:15], v16, s[4:5] offset:3072
	s_load_dwordx4 s[0:3], s[38:39], 0xd0
	s_lshr_b32 s22, s33, 6
	s_add_i32 s22, s22, s73
	s_lshl_b32 s23, s22, 11
	v_lshl_add_u32 v18, v43, 3, s23
	s_lshl_b32 s23, s22, 12
	v_lshl_add_u32 v19, v43, 4, s23
	v_mov_b32_e32 v226, 0x358637bd
	s_waitcnt lgkmcnt(0)
	s_add_u32 s8, s2, 0xb904800
	s_addc_u32 s9, s3, 0
	s_add_u32 s10, s2, 0x9804800
	s_addc_u32 s11, s3, 0
	s_mov_b64 s[12:13], s[8:9]
	s_mov_b64 s[14:15], s[10:11]
	global_load_dwordx2 v[64:65], v18, s[12:13] offset:0 nt
	global_load_dwordx2 v[66:67], v18, s[12:13] offset:512 nt
	global_load_dwordx2 v[68:69], v18, s[12:13] offset:1024 nt
	global_load_dwordx2 v[70:71], v18, s[12:13] offset:1536 nt
	global_load_dwordx2 v[72:73], v18, s[14:15] offset:0 nt
	global_load_dwordx2 v[74:75], v18, s[14:15] offset:512 nt
	global_load_dwordx2 v[76:77], v18, s[14:15] offset:1024 nt
	global_load_dwordx2 v[78:79], v18, s[14:15] offset:1536 nt
	s_add_u32 s12, s12, 0x400000
	s_addc_u32 s13, s13, 0
	s_add_u32 s14, s14, 0x400000
	s_addc_u32 s15, s15, 0
	global_load_dwordx2 v[80:81], v18, s[12:13] offset:0 nt
	global_load_dwordx2 v[82:83], v18, s[12:13] offset:512 nt
	global_load_dwordx2 v[84:85], v18, s[12:13] offset:1024 nt
	global_load_dwordx2 v[86:87], v18, s[12:13] offset:1536 nt
	global_load_dwordx2 v[88:89], v18, s[14:15] offset:0 nt
	global_load_dwordx2 v[90:91], v18, s[14:15] offset:512 nt
	global_load_dwordx2 v[92:93], v18, s[14:15] offset:1024 nt
	global_load_dwordx2 v[94:95], v18, s[14:15] offset:1536 nt
	s_add_u32 s12, s12, 0x400000
	s_addc_u32 s13, s13, 0
	s_add_u32 s14, s14, 0x400000
	s_addc_u32 s15, s15, 0
	global_load_dwordx2 v[96:97], v18, s[12:13] offset:0 nt
	global_load_dwordx2 v[98:99], v18, s[12:13] offset:512 nt
	global_load_dwordx2 v[100:101], v18, s[12:13] offset:1024 nt
	global_load_dwordx2 v[102:103], v18, s[12:13] offset:1536 nt
	global_load_dwordx2 v[104:105], v18, s[14:15] offset:0 nt
	global_load_dwordx2 v[106:107], v18, s[14:15] offset:512 nt
	global_load_dwordx2 v[108:109], v18, s[14:15] offset:1024 nt
	global_load_dwordx2 v[110:111], v18, s[14:15] offset:1536 nt
	s_add_u32 s12, s12, 0x400000
	s_addc_u32 s13, s13, 0
	s_add_u32 s14, s14, 0x400000
	s_addc_u32 s15, s15, 0
	global_load_dwordx2 v[112:113], v18, s[12:13] offset:0 nt
	global_load_dwordx2 v[114:115], v18, s[12:13] offset:512 nt
	global_load_dwordx2 v[116:117], v18, s[12:13] offset:1024 nt
	global_load_dwordx2 v[118:119], v18, s[12:13] offset:1536 nt
	global_load_dwordx2 v[120:121], v18, s[14:15] offset:0 nt
	global_load_dwordx2 v[122:123], v18, s[14:15] offset:512 nt
	global_load_dwordx2 v[124:125], v18, s[14:15] offset:1024 nt
	global_load_dwordx2 v[126:127], v18, s[14:15] offset:1536 nt
	s_add_u32 s12, s12, 0x400000
	s_addc_u32 s13, s13, 0
	s_add_u32 s14, s14, 0x400000
	s_addc_u32 s15, s15, 0
	global_load_dwordx2 v[128:129], v18, s[12:13] offset:0 nt
	global_load_dwordx2 v[130:131], v18, s[12:13] offset:512 nt
	global_load_dwordx2 v[132:133], v18, s[12:13] offset:1024 nt
	global_load_dwordx2 v[134:135], v18, s[12:13] offset:1536 nt
	global_load_dwordx2 v[136:137], v18, s[14:15] offset:0 nt
	global_load_dwordx2 v[138:139], v18, s[14:15] offset:512 nt
	global_load_dwordx2 v[140:141], v18, s[14:15] offset:1024 nt
	global_load_dwordx2 v[142:143], v18, s[14:15] offset:1536 nt
	s_add_u32 s12, s12, 0x400000
	s_addc_u32 s13, s13, 0
	s_add_u32 s14, s14, 0x400000
	s_addc_u32 s15, s15, 0
	global_load_dwordx2 v[144:145], v18, s[12:13] offset:0 nt
	global_load_dwordx2 v[146:147], v18, s[12:13] offset:512 nt
	global_load_dwordx2 v[148:149], v18, s[12:13] offset:1024 nt
	global_load_dwordx2 v[150:151], v18, s[12:13] offset:1536 nt
	global_load_dwordx2 v[152:153], v18, s[14:15] offset:0 nt
	global_load_dwordx2 v[154:155], v18, s[14:15] offset:512 nt
	global_load_dwordx2 v[156:157], v18, s[14:15] offset:1024 nt
	global_load_dwordx2 v[158:159], v18, s[14:15] offset:1536 nt
	s_waitcnt vmcnt(40)
; __device__ __forceinline__ unsigned cvt_pk_bf16(float lo, float hi) { const f32x2_t v = {lo, hi}; const bf16x2_t b = __builtin_convertvector(v, bf16x2_t); return __builtin_bit_cast(unsigned, b); }
; __device__ __forceinline__ float lo_bf(unsigned x) { return __uint_as_float(x << 16); }
; __device__ __forceinline__ float hi_bf(unsigned x) { return __uint_as_float(x & 0xffff0000u); }
; __device__ __forceinline__ void rows_proc(PR P, const int mode, const int row, const int lane, float4 (&xv)[4], const float4 (&fo)[4], const float4 (&gp)[4], const float4 (&gn)[4]) {
;     ...
;     if (mode != 0) {
;         float ss = 0.f;
; #pragma unroll
;         for (int q = 0; q < 4; ++q) ss += fo[q].x * fo[q].x + fo[q].y * fo[q].y + fo[q].z * fo[q].z + fo[q].w * fo[q].w;
;         ss = wave_sum(ss); const float r = rsqrtf(ss * (1.0f / 1024.0f) + 1e-6f) * (mode == 2 ? 1.0f : 0.5f);
; #pragma unroll
;         for (int q = 0; q < 4; ++q) {
;             xv[q].x += fo[q].x * r * gp[q].x; xv[q].y += fo[q].y * r * gp[q].y; xv[q].z += fo[q].z * r * gp[q].z; xv[q].w += fo[q].w * r * gp[q].w;
;             if (mode == 3) { const f32x4 t_ = {xv[q].x, xv[q].y, xv[q].z, xv[q].w}; __builtin_nontemporal_store(t_, (f32x4*)(P.out + (size_t)row * 1024 + (q * 64 + lane) * 4)); }
;             else { bf16_t* xo = (mode == 1 ? (bf16_t*)P.out : (bf16_t*)(P.ws + WS_FO + 34603008)) + (size_t)row * 1024; u32x2 t; t.x = pg8::cvt_pk_bf16(xv[q].x, xv[q].y); t.y = pg8::cvt_pk_bf16(xv[q].z, xv[q].w);
;                 __builtin_nontemporal_store(t, (u32x2*)(xo + (q * 64 + lane) * 4)); } }
;         if (mode == 3) return;
; __device__ __forceinline__ void rows_phase(PR P, const int mode, LAS float* ldsf, const int wv) {
;     ...
;             for (int q = 0; q < 4; ++q) {
;                 xv[q] = mode <= 1 ? R.xf[q] : make_float4(lo_bf(R.xb[q].x), hi_bf(R.xb[q].x), lo_bf(R.xb[q].y), hi_bf(R.xb[q].y));
;                 fo[q] = make_float4(lo_bf(R.fb[q].x), hi_bf(R.fb[q].x), lo_bf(R.fb[q].y), hi_bf(R.fb[q].y)); }
	v_lshlrev_b32_e32 v208, 16, v72
	v_and_b32_e32 v209, 0xffff0000, v72
	v_lshlrev_b32_e32 v210, 16, v73
	v_and_b32_e32 v211, 0xffff0000, v73
	v_lshlrev_b32_e32 v212, 16, v74
	v_and_b32_e32 v213, 0xffff0000, v74
	v_lshlrev_b32_e32 v214, 16, v75
	v_and_b32_e32 v215, 0xffff0000, v75
	v_lshlrev_b32_e32 v216, 16, v76
	v_and_b32_e32 v217, 0xffff0000, v76
	v_lshlrev_b32_e32 v218, 16, v77
	v_and_b32_e32 v219, 0xffff0000, v77
	v_lshlrev_b32_e32 v220, 16, v78
	v_and_b32_e32 v221, 0xffff0000, v78
	v_lshlrev_b32_e32 v222, 16, v79
	v_and_b32_e32 v223, 0xffff0000, v79
	v_pk_mul_f32 v[224:225], v[208:209], v[208:209]
	v_pk_fma_f32 v[224:225], v[210:211], v[210:211], v[224:225]
	v_pk_fma_f32 v[224:225], v[212:213], v[212:213], v[224:225]
	v_pk_fma_f32 v[224:225], v[214:215], v[214:215], v[224:225]
	v_pk_fma_f32 v[224:225], v[216:217], v[216:217], v[224:225]
	v_pk_fma_f32 v[224:225], v[218:219], v[218:219], v[224:225]
	v_pk_fma_f32 v[224:225], v[220:221], v[220:221], v[224:225]
	v_pk_fma_f32 v[224:225], v[222:223], v[222:223], v[224:225]
	v_add_f32_e32 v224, v224, v225
	v_lshlrev_b32_e32 v192, 16, v64
	v_and_b32_e32 v193, 0xffff0000, v64
	v_lshlrev_b32_e32 v194, 16, v65
	v_and_b32_e32 v195, 0xffff0000, v65
	v_add_f32_dpp v224, v224, v224 quad_perm:[1,0,3,2] row_mask:0xf bank_mask:0xf bound_ctrl:1
	v_lshlrev_b32_e32 v196, 16, v66
	v_and_b32_e32 v197, 0xffff0000, v66
	v_lshlrev_b32_e32 v198, 16, v67
	v_and_b32_e32 v199, 0xffff0000, v67
	v_add_f32_dpp v224, v224, v224 quad_perm:[2,3,0,1] row_mask:0xf bank_mask:0xf bound_ctrl:1
	v_lshlrev_b32_e32 v200, 16, v68
	v_and_b32_e32 v201, 0xffff0000, v68
	v_lshlrev_b32_e32 v202, 16, v69
	v_and_b32_e32 v203, 0xffff0000, v69
	v_add_f32_dpp v224, v224, v224 row_half_mirror row_mask:0xf bank_mask:0xf bound_ctrl:1
	v_lshlrev_b32_e32 v204, 16, v70
	v_and_b32_e32 v205, 0xffff0000, v70
	v_lshlrev_b32_e32 v206, 16, v71
	v_and_b32_e32 v207, 0xffff0000, v71
	v_add_f32_dpp v224, v224, v224 row_mirror row_mask:0xf bank_mask:0xf bound_ctrl:1
	s_nop 0
	v_readlane_b32 s16, v224, 0
	v_readlane_b32 s17, v224, 16
	v_readlane_b32 s18, v224, 32
	v_readlane_b32 s19, v224, 48
	s_nop 1
	v_mov_b32_e32 v224, s17
	v_add_f32_e32 v224, s16, v224
	v_add_f32_e32 v224, s18, v224
	v_add_f32_e32 v224, s19, v224
	v_fmamk_f32 v224, v224, 0x3a800000, v226
	v_rsq_f32_e32 v224, v224
	s_nop 0
	v_mul_f32_e32 v224, 0.5, v224
	v_pk_mul_f32 v[208:209], v[224:225], v[208:209] op_sel_hi:[0,1]
	v_pk_mul_f32 v[210:211], v[224:225], v[210:211] op_sel_hi:[0,1]
	v_pk_mul_f32 v[212:213], v[224:225], v[212:213] op_sel_hi:[0,1]
	v_pk_mul_f32 v[214:215], v[224:225], v[214:215] op_sel_hi:[0,1]
	v_pk_mul_f32 v[216:217], v[224:225], v[216:217] op_sel_hi:[0,1]
	v_pk_mul_f32 v[218:219], v[224:225], v[218:219] op_sel_hi:[0,1]
	v_pk_mul_f32 v[220:221], v[224:225], v[220:221] op_sel_hi:[0,1]
	v_pk_mul_f32 v[222:223], v[224:225], v[222:223] op_sel_hi:[0,1]
	v_pk_fma_f32 v[192:193], v[0:1], v[208:209], v[192:193]
	v_pk_fma_f32 v[194:195], v[2:3], v[210:211], v[194:195]
	v_pk_fma_f32 v[196:197], v[4:5], v[212:213], v[196:197]
	v_pk_fma_f32 v[198:199], v[6:7], v[214:215], v[198:199]
	v_pk_fma_f32 v[200:201], v[8:9], v[216:217], v[200:201]
	v_pk_fma_f32 v[202:203], v[10:11], v[218:219], v[202:203]
	v_pk_fma_f32 v[204:205], v[12:13], v[220:221], v[204:205]
	v_pk_fma_f32 v[206:207], v[14:15], v[222:223], v[206:207]
	s_mov_b64 s[20:21], s[0:1]
	global_store_dwordx4 v19, v[192:195], s[20:21] offset:0 nt
	global_store_dwordx4 v19, v[196:199], s[20:21] offset:1024 nt
	global_store_dwordx4 v19, v[200:203], s[20:21] offset:2048 nt
	global_store_dwordx4 v19, v[204:207], s[20:21] offset:3072 nt
	s_add_u32 s12, s12, 0x400000
	s_addc_u32 s13, s13, 0
	s_add_u32 s14, s14, 0x400000
	s_addc_u32 s15, s15, 0
	global_load_dwordx2 v[64:65], v18, s[12:13] offset:0 nt
	global_load_dwordx2 v[66:67], v18, s[12:13] offset:512 nt
	global_load_dwordx2 v[68:69], v18, s[12:13] offset:1024 nt
	global_load_dwordx2 v[70:71], v18, s[12:13] offset:1536 nt
	global_load_dwordx2 v[72:73], v18, s[14:15] offset:0 nt
	global_load_dwordx2 v[74:75], v18, s[14:15] offset:512 nt
	global_load_dwordx2 v[76:77], v18, s[14:15] offset:1024 nt
	global_load_dwordx2 v[78:79], v18, s[14:15] offset:1536 nt
	s_waitcnt vmcnt(44)
	v_lshlrev_b32_e32 v208, 16, v88
	v_and_b32_e32 v209, 0xffff0000, v88
	v_lshlrev_b32_e32 v210, 16, v89
	v_and_b32_e32 v211, 0xffff0000, v89
	v_lshlrev_b32_e32 v212, 16, v90
	v_and_b32_e32 v213, 0xffff0000, v90
	v_lshlrev_b32_e32 v214, 16, v91
	v_and_b32_e32 v215, 0xffff0000, v91
	v_lshlrev_b32_e32 v216, 16, v92
	v_and_b32_e32 v217, 0xffff0000, v92
	v_lshlrev_b32_e32 v218, 16, v93
	v_and_b32_e32 v219, 0xffff0000, v93
	v_lshlrev_b32_e32 v220, 16, v94
	v_and_b32_e32 v221, 0xffff0000, v94
	v_lshlrev_b32_e32 v222, 16, v95
	v_and_b32_e32 v223, 0xffff0000, v95
	v_pk_mul_f32 v[224:225], v[208:209], v[208:209]
	v_pk_fma_f32 v[224:225], v[210:211], v[210:211], v[224:225]
	v_pk_fma_f32 v[224:225], v[212:213], v[212:213], v[224:225]
	v_pk_fma_f32 v[224:225], v[214:215], v[214:215], v[224:225]
	v_pk_fma_f32 v[224:225], v[216:217], v[216:217], v[224:225]
	v_pk_fma_f32 v[224:225], v[218:219], v[218:219], v[224:225]
	v_pk_fma_f32 v[224:225], v[220:221], v[220:221], v[224:225]
	v_pk_fma_f32 v[224:225], v[222:223], v[222:223], v[224:225]
	v_add_f32_e32 v224, v224, v225
	v_lshlrev_b32_e32 v192, 16, v80
	v_and_b32_e32 v193, 0xffff0000, v80
	v_lshlrev_b32_e32 v194, 16, v81
	v_and_b32_e32 v195, 0xffff0000, v81
	v_add_f32_dpp v224, v224, v224 quad_perm:[1,0,3,2] row_mask:0xf bank_mask:0xf bound_ctrl:1
	v_lshlrev_b32_e32 v196, 16, v82
	v_and_b32_e32 v197, 0xffff0000, v82
	v_lshlrev_b32_e32 v198, 16, v83
	v_and_b32_e32 v199, 0xffff0000, v83
; __device__ __forceinline__ unsigned cvt_pk_bf16(float lo, float hi) { const f32x2_t v = {lo, hi}; const bf16x2_t b = __builtin_convertvector(v, bf16x2_t); return __builtin_bit_cast(unsigned, b); }
; __device__ __forceinline__ float lo_bf(unsigned x) { return __uint_as_float(x << 16); }
; __device__ __forceinline__ float hi_bf(unsigned x) { return __uint_as_float(x & 0xffff0000u); }
; __device__ __forceinline__ void rows_proc(PR P, const int mode, const int row, const int lane, float4 (&xv)[4], const float4 (&fo)[4], const float4 (&gp)[4], const float4 (&gn)[4]) {
;     ...
;     if (mode != 0) {
;         float ss = 0.f;
; #pragma unroll
;         for (int q = 0; q < 4; ++q) ss += fo[q].x * fo[q].x + fo[q].y * fo[q].y + fo[q].z * fo[q].z + fo[q].w * fo[q].w;
;         ss = wave_sum(ss); const float r = rsqrtf(ss * (1.0f / 1024.0f) + 1e-6f) * (mode == 2 ? 1.0f : 0.5f);
; #pragma unroll
;         for (int q = 0; q < 4; ++q) {
;             xv[q].x += fo[q].x * r * gp[q].x; xv[q].y += fo[q].y * r * gp[q].y; xv[q].z += fo[q].z * r * gp[q].z; xv[q].w += fo[q].w * r * gp[q].w;
;             if (mode == 3) { const f32x4 t_ = {xv[q].x, xv[q].y, xv[q].z, xv[q].w}; __builtin_nontemporal_store(t_, (f32x4*)(P.out + (size_t)row * 1024 + (q * 64 + lane) * 4)); }
;             else { bf16_t* xo = (mode == 1 ? (bf16_t*)P.out : (bf16_t*)(P.ws + WS_FO + 34603008)) + (size_t)row * 1024; u32x2 t; t.x = pg8::cvt_pk_bf16(xv[q].x, xv[q].y); t.y = pg8::cvt_pk_bf16(xv[q].z, xv[q].w);
;                 __builtin_nontemporal_store(t, (u32x2*)(xo + (q * 64 + lane) * 4)); } }
;         if (mode == 3) return;
; __device__ __forceinline__ void rows_phase(PR P, const int mode, LAS float* ldsf, const int wv) {
;     ...
;             for (int q = 0; q < 4; ++q) {
;                 xv[q] = mode <= 1 ? R.xf[q] : make_float4(lo_bf(R.xb[q].x), hi_bf(R.xb[q].x), lo_bf(R.xb[q].y), hi_bf(R.xb[q].y));
;                 fo[q] = make_float4(lo_bf(R.fb[q].x), hi_bf(R.fb[q].x), lo_bf(R.fb[q].y), hi_bf(R.fb[q].y)); }
	v_add_f32_dpp v224, v224, v224 quad_perm:[2,3,0,1] row_mask:0xf bank_mask:0xf bound_ctrl:1
	v_lshlrev_b32_e32 v200, 16, v84
	v_and_b32_e32 v201, 0xffff0000, v84
	v_lshlrev_b32_e32 v202, 16, v85
	v_and_b32_e32 v203, 0xffff0000, v85
	v_add_f32_dpp v224, v224, v224 row_half_mirror row_mask:0xf bank_mask:0xf bound_ctrl:1
	v_lshlrev_b32_e32 v204, 16, v86
	v_and_b32_e32 v205, 0xffff0000, v86
	v_lshlrev_b32_e32 v206, 16, v87
	v_and_b32_e32 v207, 0xffff0000, v87
	v_add_f32_dpp v224, v224, v224 row_mirror row_mask:0xf bank_mask:0xf bound_ctrl:1
	s_nop 0
	v_readlane_b32 s16, v224, 0
	v_readlane_b32 s17, v224, 16
	v_readlane_b32 s18, v224, 32
	v_readlane_b32 s19, v224, 48
	s_nop 1
	v_mov_b32_e32 v224, s17
	v_add_f32_e32 v224, s16, v224
	v_add_f32_e32 v224, s18, v224
	v_add_f32_e32 v224, s19, v224
	v_fmamk_f32 v224, v224, 0x3a800000, v226
	v_rsq_f32_e32 v224, v224
	s_nop 0
	v_mul_f32_e32 v224, 0.5, v224
	v_pk_mul_f32 v[208:209], v[224:225], v[208:209] op_sel_hi:[0,1]
	v_pk_mul_f32 v[210:211], v[224:225], v[210:211] op_sel_hi:[0,1]
	v_pk_mul_f32 v[212:213], v[224:225], v[212:213] op_sel_hi:[0,1]
	v_pk_mul_f32 v[214:215], v[224:225], v[214:215] op_sel_hi:[0,1]
	v_pk_mul_f32 v[216:217], v[224:225], v[216:217] op_sel_hi:[0,1]
	v_pk_mul_f32 v[218:219], v[224:225], v[218:219] op_sel_hi:[0,1]
	v_pk_mul_f32 v[220:221], v[224:225], v[220:221] op_sel_hi:[0,1]
	v_pk_mul_f32 v[222:223], v[224:225], v[222:223] op_sel_hi:[0,1]
	v_pk_fma_f32 v[192:193], v[0:1], v[208:209], v[192:193]
	v_pk_fma_f32 v[194:195], v[2:3], v[210:211], v[194:195]
	v_pk_fma_f32 v[196:197], v[4:5], v[212:213], v[196:197]
	v_pk_fma_f32 v[198:199], v[6:7], v[214:215], v[198:199]
	v_pk_fma_f32 v[200:201], v[8:9], v[216:217], v[200:201]
	v_pk_fma_f32 v[202:203], v[10:11], v[218:219], v[202:203]
	v_pk_fma_f32 v[204:205], v[12:13], v[220:221], v[204:205]
	v_pk_fma_f32 v[206:207], v[14:15], v[222:223], v[206:207]
	s_add_u32 s20, s20, 0x800000
	s_addc_u32 s21, s21, 0
	global_store_dwordx4 v19, v[192:195], s[20:21] offset:0 nt
	global_store_dwordx4 v19, v[196:199], s[20:21] offset:1024 nt
	global_store_dwordx4 v19, v[200:203], s[20:21] offset:2048 nt
	global_store_dwordx4 v19, v[204:207], s[20:21] offset:3072 nt
	s_add_u32 s12, s12, 0x400000
	s_addc_u32 s13, s13, 0
	s_add_u32 s14, s14, 0x400000
	s_addc_u32 s15, s15, 0
	global_load_dwordx2 v[80:81], v18, s[12:13] offset:0 nt
	global_load_dwordx2 v[82:83], v18, s[12:13] offset:512 nt
	global_load_dwordx2 v[84:85], v18, s[12:13] offset:1024 nt
	global_load_dwordx2 v[86:87], v18, s[12:13] offset:1536 nt
	global_load_dwordx2 v[88:89], v18, s[14:15] offset:0 nt
	global_load_dwordx2 v[90:91], v18, s[14:15] offset:512 nt
	global_load_dwordx2 v[92:93], v18, s[14:15] offset:1024 nt
	global_load_dwordx2 v[94:95], v18, s[14:15] offset:1536 nt
	s_waitcnt vmcnt(48)
	v_lshlrev_b32_e32 v208, 16, v104
	v_and_b32_e32 v209, 0xffff0000, v104
	v_lshlrev_b32_e32 v210, 16, v105
	v_and_b32_e32 v211, 0xffff0000, v105
	v_lshlrev_b32_e32 v212, 16, v106
	v_and_b32_e32 v213, 0xffff0000, v106
	v_lshlrev_b32_e32 v214, 16, v107
	v_and_b32_e32 v215, 0xffff0000, v107
	v_lshlrev_b32_e32 v216, 16, v108
	v_and_b32_e32 v217, 0xffff0000, v108
	v_lshlrev_b32_e32 v218, 16, v109
	v_and_b32_e32 v219, 0xffff0000, v109
	v_lshlrev_b32_e32 v220, 16, v110
	v_and_b32_e32 v221, 0xffff0000, v110
	v_lshlrev_b32_e32 v222, 16, v111
	v_and_b32_e32 v223, 0xffff0000, v111
	v_pk_mul_f32 v[224:225], v[208:209], v[208:209]
	v_pk_fma_f32 v[224:225], v[210:211], v[210:211], v[224:225]
	v_pk_fma_f32 v[224:225], v[212:213], v[212:213], v[224:225]
	v_pk_fma_f32 v[224:225], v[214:215], v[214:215], v[224:225]
	v_pk_fma_f32 v[224:225], v[216:217], v[216:217], v[224:225]
	v_pk_fma_f32 v[224:225], v[218:219], v[218:219], v[224:225]
	v_pk_fma_f32 v[224:225], v[220:221], v[220:221], v[224:225]
	v_pk_fma_f32 v[224:225], v[222:223], v[222:223], v[224:225]
	v_add_f32_e32 v224, v224, v225
	v_lshlrev_b32_e32 v192, 16, v96
	v_and_b32_e32 v193, 0xffff0000, v96
	v_lshlrev_b32_e32 v194, 16, v97
	v_and_b32_e32 v195, 0xffff0000, v97
	v_add_f32_dpp v224, v224, v224 quad_perm:[1,0,3,2] row_mask:0xf bank_mask:0xf bound_ctrl:1
	v_lshlrev_b32_e32 v196, 16, v98
	v_and_b32_e32 v197, 0xffff0000, v98
	v_lshlrev_b32_e32 v198, 16, v99
	v_and_b32_e32 v199, 0xffff0000, v99
	v_add_f32_dpp v224, v224, v224 quad_perm:[2,3,0,1] row_mask:0xf bank_mask:0xf bound_ctrl:1
	v_lshlrev_b32_e32 v200, 16, v100
	v_and_b32_e32 v201, 0xffff0000, v100
	v_lshlrev_b32_e32 v202, 16, v101
	v_and_b32_e32 v203, 0xffff0000, v101
	v_add_f32_dpp v224, v224, v224 row_half_mirror row_mask:0xf bank_mask:0xf bound_ctrl:1
	v_lshlrev_b32_e32 v204, 16, v102
	v_and_b32_e32 v205, 0xffff0000, v102
	v_lshlrev_b32_e32 v206, 16, v103
	v_and_b32_e32 v207, 0xffff0000, v103
	v_add_f32_dpp v224, v224, v224 row_mirror row_mask:0xf bank_mask:0xf bound_ctrl:1
	s_nop 0
	v_readlane_b32 s16, v224, 0
	v_readlane_b32 s17, v224, 16
	v_readlane_b32 s18, v224, 32
	v_readlane_b32 s19, v224, 48
	s_nop 1
	v_mov_b32_e32 v224, s17
	v_add_f32_e32 v224, s16, v224
	v_add_f32_e32 v224, s18, v224
	v_add_f32_e32 v224, s19, v224
	v_fmamk_f32 v224, v224, 0x3a800000, v226
	v_rsq_f32_e32 v224, v224
	s_nop 0
	v_mul_f32_e32 v224, 0.5, v224
	v_pk_mul_f32 v[208:209], v[224:225], v[208:209] op_sel_hi:[0,1]
	v_pk_mul_f32 v[210:211], v[224:225], v[210:211] op_sel_hi:[0,1]
	v_pk_mul_f32 v[212:213], v[224:225], v[212:213] op_sel_hi:[0,1]
	v_pk_mul_f32 v[214:215], v[224:225], v[214:215] op_sel_hi:[0,1]
	v_pk_mul_f32 v[216:217], v[224:225], v[216:217] op_sel_hi:[0,1]
	v_pk_mul_f32 v[218:219], v[224:225], v[218:219] op_sel_hi:[0,1]
	v_pk_mul_f32 v[220:221], v[224:225], v[220:221] op_sel_hi:[0,1]
	v_pk_mul_f32 v[222:223], v[224:225], v[222:223] op_sel_hi:[0,1]
	v_pk_fma_f32 v[192:193], v[0:1], v[208:209], v[192:193]
	v_pk_fma_f32 v[194:195], v[2:3], v[210:211], v[194:195]
	v_pk_fma_f32 v[196:197], v[4:5], v[212:213], v[196:197]
	v_pk_fma_f32 v[198:199], v[6:7], v[214:215], v[198:199]
	v_pk_fma_f32 v[200:201], v[8:9], v[216:217], v[200:201]
	v_pk_fma_f32 v[202:203], v[10:11], v[218:219], v[202:203]
	v_pk_fma_f32 v[204:205], v[12:13], v[220:221], v[204:205]
	v_pk_fma_f32 v[206:207], v[14:15], v[222:223], v[206:207]
	s_add_u32 s20, s20, 0x800000
	s_addc_u32 s21, s21, 0
	global_store_dwordx4 v19, v[192:195], s[20:21] offset:0 nt
	global_store_dwordx4 v19, v[196:199], s[20:21] offset:1024 nt
	global_store_dwordx4 v19, v[200:203], s[20:21] offset:2048 nt
	global_store_dwordx4 v19, v[204:207], s[20:21] offset:3072 nt
	s_waitcnt vmcnt(44)
; __device__ __forceinline__ unsigned cvt_pk_bf16(float lo, float hi) { const f32x2_t v = {lo, hi}; const bf16x2_t b = __builtin_convertvector(v, bf16x2_t); return __builtin_bit_cast(unsigned, b); }
; __device__ __forceinline__ float lo_bf(unsigned x) { return __uint_as_float(x << 16); }
; __device__ __forceinline__ float hi_bf(unsigned x) { return __uint_as_float(x & 0xffff0000u); }
; __device__ __forceinline__ void rows_proc(PR P, const int mode, const int row, const int lane, float4 (&xv)[4], const float4 (&fo)[4], const float4 (&gp)[4], const float4 (&gn)[4]) {
;     ...
;     if (mode != 0) {
;         float ss = 0.f;
; #pragma unroll
;         for (int q = 0; q < 4; ++q) ss += fo[q].x * fo[q].x + fo[q].y * fo[q].y + fo[q].z * fo[q].z + fo[q].w * fo[q].w;
;         ss = wave_sum(ss); const float r = rsqrtf(ss * (1.0f / 1024.0f) + 1e-6f) * (mode == 2 ? 1.0f : 0.5f);
; #pragma unroll
;         for (int q = 0; q < 4; ++q) {
;             xv[q].x += fo[q].x * r * gp[q].x; xv[q].y += fo[q].y * r * gp[q].y; xv[q].z += fo[q].z * r * gp[q].z; xv[q].w += fo[q].w * r * gp[q].w;
;             if (mode == 3) { const f32x4 t_ = {xv[q].x, xv[q].y, xv[q].z, xv[q].w}; __builtin_nontemporal_store(t_, (f32x4*)(P.out + (size_t)row * 1024 + (q * 64 + lane) * 4)); }
;             else { bf16_t* xo = (mode == 1 ? (bf16_t*)P.out : (bf16_t*)(P.ws + WS_FO + 34603008)) + (size_t)row * 1024; u32x2 t; t.x = pg8::cvt_pk_bf16(xv[q].x, xv[q].y); t.y = pg8::cvt_pk_bf16(xv[q].z, xv[q].w);
;                 __builtin_nontemporal_store(t, (u32x2*)(xo + (q * 64 + lane) * 4)); } }
;         if (mode == 3) return;
; __device__ __forceinline__ void rows_phase(PR P, const int mode, LAS float* ldsf, const int wv) {
;     ...
;             for (int q = 0; q < 4; ++q) {
;                 xv[q] = mode <= 1 ? R.xf[q] : make_float4(lo_bf(R.xb[q].x), hi_bf(R.xb[q].x), lo_bf(R.xb[q].y), hi_bf(R.xb[q].y));
;                 fo[q] = make_float4(lo_bf(R.fb[q].x), hi_bf(R.fb[q].x), lo_bf(R.fb[q].y), hi_bf(R.fb[q].y)); }
	v_lshlrev_b32_e32 v208, 16, v120
	v_and_b32_e32 v209, 0xffff0000, v120
	v_lshlrev_b32_e32 v210, 16, v121
	v_and_b32_e32 v211, 0xffff0000, v121
	v_lshlrev_b32_e32 v212, 16, v122
	v_and_b32_e32 v213, 0xffff0000, v122
	v_lshlrev_b32_e32 v214, 16, v123
	v_and_b32_e32 v215, 0xffff0000, v123
	v_lshlrev_b32_e32 v216, 16, v124
	v_and_b32_e32 v217, 0xffff0000, v124
	v_lshlrev_b32_e32 v218, 16, v125
	v_and_b32_e32 v219, 0xffff0000, v125
	v_lshlrev_b32_e32 v220, 16, v126
	v_and_b32_e32 v221, 0xffff0000, v126
	v_lshlrev_b32_e32 v222, 16, v127
	v_and_b32_e32 v223, 0xffff0000, v127
	v_pk_mul_f32 v[224:225], v[208:209], v[208:209]
	v_pk_fma_f32 v[224:225], v[210:211], v[210:211], v[224:225]
	v_pk_fma_f32 v[224:225], v[212:213], v[212:213], v[224:225]
	v_pk_fma_f32 v[224:225], v[214:215], v[214:215], v[224:225]
	v_pk_fma_f32 v[224:225], v[216:217], v[216:217], v[224:225]
	v_pk_fma_f32 v[224:225], v[218:219], v[218:219], v[224:225]
	v_pk_fma_f32 v[224:225], v[220:221], v[220:221], v[224:225]
	v_pk_fma_f32 v[224:225], v[222:223], v[222:223], v[224:225]
	v_add_f32_e32 v224, v224, v225
	v_lshlrev_b32_e32 v192, 16, v112
	v_and_b32_e32 v193, 0xffff0000, v112
	v_lshlrev_b32_e32 v194, 16, v113
	v_and_b32_e32 v195, 0xffff0000, v113
	v_add_f32_dpp v224, v224, v224 quad_perm:[1,0,3,2] row_mask:0xf bank_mask:0xf bound_ctrl:1
	v_lshlrev_b32_e32 v196, 16, v114
	v_and_b32_e32 v197, 0xffff0000, v114
	v_lshlrev_b32_e32 v198, 16, v115
	v_and_b32_e32 v199, 0xffff0000, v115
	v_add_f32_dpp v224, v224, v224 quad_perm:[2,3,0,1] row_mask:0xf bank_mask:0xf bound_ctrl:1
	v_lshlrev_b32_e32 v200, 16, v116
	v_and_b32_e32 v201, 0xffff0000, v116
	v_lshlrev_b32_e32 v202, 16, v117
	v_and_b32_e32 v203, 0xffff0000, v117
	v_add_f32_dpp v224, v224, v224 row_half_mirror row_mask:0xf bank_mask:0xf bound_ctrl:1
	v_lshlrev_b32_e32 v204, 16, v118
	v_and_b32_e32 v205, 0xffff0000, v118
	v_lshlrev_b32_e32 v206, 16, v119
	v_and_b32_e32 v207, 0xffff0000, v119
	v_add_f32_dpp v224, v224, v224 row_mirror row_mask:0xf bank_mask:0xf bound_ctrl:1
	s_nop 0
	v_readlane_b32 s16, v224, 0
	v_readlane_b32 s17, v224, 16
	v_readlane_b32 s18, v224, 32
	v_readlane_b32 s19, v224, 48
	s_nop 1
	v_mov_b32_e32 v224, s17
	v_add_f32_e32 v224, s16, v224
	v_add_f32_e32 v224, s18, v224
	v_add_f32_e32 v224, s19, v224
	v_fmamk_f32 v224, v224, 0x3a800000, v226
	v_rsq_f32_e32 v224, v224
	s_nop 0
	v_mul_f32_e32 v224, 0.5, v224
	v_pk_mul_f32 v[208:209], v[224:225], v[208:209] op_sel_hi:[0,1]
	v_pk_mul_f32 v[210:211], v[224:225], v[210:211] op_sel_hi:[0,1]
	v_pk_mul_f32 v[212:213], v[224:225], v[212:213] op_sel_hi:[0,1]
	v_pk_mul_f32 v[214:215], v[224:225], v[214:215] op_sel_hi:[0,1]
	v_pk_mul_f32 v[216:217], v[224:225], v[216:217] op_sel_hi:[0,1]
	v_pk_mul_f32 v[218:219], v[224:225], v[218:219] op_sel_hi:[0,1]
	v_pk_mul_f32 v[220:221], v[224:225], v[220:221] op_sel_hi:[0,1]
	v_pk_mul_f32 v[222:223], v[224:225], v[222:223] op_sel_hi:[0,1]
	v_pk_fma_f32 v[192:193], v[0:1], v[208:209], v[192:193]
	v_pk_fma_f32 v[194:195], v[2:3], v[210:211], v[194:195]
	v_pk_fma_f32 v[196:197], v[4:5], v[212:213], v[196:197]
	v_pk_fma_f32 v[198:199], v[6:7], v[214:215], v[198:199]
	v_pk_fma_f32 v[200:201], v[8:9], v[216:217], v[200:201]
	v_pk_fma_f32 v[202:203], v[10:11], v[218:219], v[202:203]
	v_pk_fma_f32 v[204:205], v[12:13], v[220:221], v[204:205]
	v_pk_fma_f32 v[206:207], v[14:15], v[222:223], v[206:207]
	s_add_u32 s20, s20, 0x800000
	s_addc_u32 s21, s21, 0
	global_store_dwordx4 v19, v[192:195], s[20:21] offset:0 nt
	global_store_dwordx4 v19, v[196:199], s[20:21] offset:1024 nt
	global_store_dwordx4 v19, v[200:203], s[20:21] offset:2048 nt
	global_store_dwordx4 v19, v[204:207], s[20:21] offset:3072 nt
	s_waitcnt vmcnt(40)
	v_lshlrev_b32_e32 v208, 16, v136
	v_and_b32_e32 v209, 0xffff0000, v136
	v_lshlrev_b32_e32 v210, 16, v137
	v_and_b32_e32 v211, 0xffff0000, v137
	v_lshlrev_b32_e32 v212, 16, v138
	v_and_b32_e32 v213, 0xffff0000, v138
	v_lshlrev_b32_e32 v214, 16, v139
	v_and_b32_e32 v215, 0xffff0000, v139
	v_lshlrev_b32_e32 v216, 16, v140
	v_and_b32_e32 v217, 0xffff0000, v140
	v_lshlrev_b32_e32 v218, 16, v141
	v_and_b32_e32 v219, 0xffff0000, v141
	v_lshlrev_b32_e32 v220, 16, v142
	v_and_b32_e32 v221, 0xffff0000, v142
	v_lshlrev_b32_e32 v222, 16, v143
	v_and_b32_e32 v223, 0xffff0000, v143
	v_pk_mul_f32 v[224:225], v[208:209], v[208:209]
	v_pk_fma_f32 v[224:225], v[210:211], v[210:211], v[224:225]
	v_pk_fma_f32 v[224:225], v[212:213], v[212:213], v[224:225]
	v_pk_fma_f32 v[224:225], v[214:215], v[214:215], v[224:225]
	v_pk_fma_f32 v[224:225], v[216:217], v[216:217], v[224:225]
	v_pk_fma_f32 v[224:225], v[218:219], v[218:219], v[224:225]
	v_pk_fma_f32 v[224:225], v[220:221], v[220:221], v[224:225]
	v_pk_fma_f32 v[224:225], v[222:223], v[222:223], v[224:225]
	v_add_f32_e32 v224, v224, v225
	v_lshlrev_b32_e32 v192, 16, v128
	v_and_b32_e32 v193, 0xffff0000, v128
	v_lshlrev_b32_e32 v194, 16, v129
	v_and_b32_e32 v195, 0xffff0000, v129
	v_add_f32_dpp v224, v224, v224 quad_perm:[1,0,3,2] row_mask:0xf bank_mask:0xf bound_ctrl:1
	v_lshlrev_b32_e32 v196, 16, v130
	v_and_b32_e32 v197, 0xffff0000, v130
	v_lshlrev_b32_e32 v198, 16, v131
	v_and_b32_e32 v199, 0xffff0000, v131
	v_add_f32_dpp v224, v224, v224 quad_perm:[2,3,0,1] row_mask:0xf bank_mask:0xf bound_ctrl:1
	v_lshlrev_b32_e32 v200, 16, v132
	v_and_b32_e32 v201, 0xffff0000, v132
	v_lshlrev_b32_e32 v202, 16, v133
	v_and_b32_e32 v203, 0xffff0000, v133
	v_add_f32_dpp v224, v224, v224 row_half_mirror row_mask:0xf bank_mask:0xf bound_ctrl:1
	v_lshlrev_b32_e32 v204, 16, v134
	v_and_b32_e32 v205, 0xffff0000, v134
	v_lshlrev_b32_e32 v206, 16, v135
	v_and_b32_e32 v207, 0xffff0000, v135
; __device__ __forceinline__ unsigned cvt_pk_bf16(float lo, float hi) { const f32x2_t v = {lo, hi}; const bf16x2_t b = __builtin_convertvector(v, bf16x2_t); return __builtin_bit_cast(unsigned, b); }
; __device__ __forceinline__ float lo_bf(unsigned x) { return __uint_as_float(x << 16); }
; __device__ __forceinline__ float hi_bf(unsigned x) { return __uint_as_float(x & 0xffff0000u); }
; __device__ __forceinline__ void rows_proc(PR P, const int mode, const int row, const int lane, float4 (&xv)[4], const float4 (&fo)[4], const float4 (&gp)[4], const float4 (&gn)[4]) {
;     ...
;     if (mode != 0) {
;         float ss = 0.f;
; #pragma unroll
;         for (int q = 0; q < 4; ++q) ss += fo[q].x * fo[q].x + fo[q].y * fo[q].y + fo[q].z * fo[q].z + fo[q].w * fo[q].w;
;         ss = wave_sum(ss); const float r = rsqrtf(ss * (1.0f / 1024.0f) + 1e-6f) * (mode == 2 ? 1.0f : 0.5f);
; #pragma unroll
;         for (int q = 0; q < 4; ++q) {
;             xv[q].x += fo[q].x * r * gp[q].x; xv[q].y += fo[q].y * r * gp[q].y; xv[q].z += fo[q].z * r * gp[q].z; xv[q].w += fo[q].w * r * gp[q].w;
;             if (mode == 3) { const f32x4 t_ = {xv[q].x, xv[q].y, xv[q].z, xv[q].w}; __builtin_nontemporal_store(t_, (f32x4*)(P.out + (size_t)row * 1024 + (q * 64 + lane) * 4)); }
;             else { bf16_t* xo = (mode == 1 ? (bf16_t*)P.out : (bf16_t*)(P.ws + WS_FO + 34603008)) + (size_t)row * 1024; u32x2 t; t.x = pg8::cvt_pk_bf16(xv[q].x, xv[q].y); t.y = pg8::cvt_pk_bf16(xv[q].z, xv[q].w);
;                 __builtin_nontemporal_store(t, (u32x2*)(xo + (q * 64 + lane) * 4)); } }
;         if (mode == 3) return;
; __device__ __forceinline__ void rows_phase(PR P, const int mode, LAS float* ldsf, const int wv) {
;     ...
;             for (int q = 0; q < 4; ++q) {
;                 xv[q] = mode <= 1 ? R.xf[q] : make_float4(lo_bf(R.xb[q].x), hi_bf(R.xb[q].x), lo_bf(R.xb[q].y), hi_bf(R.xb[q].y));
;                 fo[q] = make_float4(lo_bf(R.fb[q].x), hi_bf(R.fb[q].x), lo_bf(R.fb[q].y), hi_bf(R.fb[q].y)); }
	v_add_f32_dpp v224, v224, v224 row_mirror row_mask:0xf bank_mask:0xf bound_ctrl:1
	s_nop 0
	v_readlane_b32 s16, v224, 0
	v_readlane_b32 s17, v224, 16
	v_readlane_b32 s18, v224, 32
	v_readlane_b32 s19, v224, 48
	s_nop 1
	v_mov_b32_e32 v224, s17
	v_add_f32_e32 v224, s16, v224
	v_add_f32_e32 v224, s18, v224
	v_add_f32_e32 v224, s19, v224
	v_fmamk_f32 v224, v224, 0x3a800000, v226
	v_rsq_f32_e32 v224, v224
	s_nop 0
	v_mul_f32_e32 v224, 0.5, v224
	v_pk_mul_f32 v[208:209], v[224:225], v[208:209] op_sel_hi:[0,1]
	v_pk_mul_f32 v[210:211], v[224:225], v[210:211] op_sel_hi:[0,1]
	v_pk_mul_f32 v[212:213], v[224:225], v[212:213] op_sel_hi:[0,1]
	v_pk_mul_f32 v[214:215], v[224:225], v[214:215] op_sel_hi:[0,1]
	v_pk_mul_f32 v[216:217], v[224:225], v[216:217] op_sel_hi:[0,1]
	v_pk_mul_f32 v[218:219], v[224:225], v[218:219] op_sel_hi:[0,1]
	v_pk_mul_f32 v[220:221], v[224:225], v[220:221] op_sel_hi:[0,1]
	v_pk_mul_f32 v[222:223], v[224:225], v[222:223] op_sel_hi:[0,1]
	v_pk_fma_f32 v[192:193], v[0:1], v[208:209], v[192:193]
	v_pk_fma_f32 v[194:195], v[2:3], v[210:211], v[194:195]
	v_pk_fma_f32 v[196:197], v[4:5], v[212:213], v[196:197]
	v_pk_fma_f32 v[198:199], v[6:7], v[214:215], v[198:199]
	v_pk_fma_f32 v[200:201], v[8:9], v[216:217], v[200:201]
	v_pk_fma_f32 v[202:203], v[10:11], v[218:219], v[202:203]
	v_pk_fma_f32 v[204:205], v[12:13], v[220:221], v[204:205]
	v_pk_fma_f32 v[206:207], v[14:15], v[222:223], v[206:207]
	s_add_u32 s20, s20, 0x800000
	s_addc_u32 s21, s21, 0
	global_store_dwordx4 v19, v[192:195], s[20:21] offset:0 nt
	global_store_dwordx4 v19, v[196:199], s[20:21] offset:1024 nt
	global_store_dwordx4 v19, v[200:203], s[20:21] offset:2048 nt
	global_store_dwordx4 v19, v[204:207], s[20:21] offset:3072 nt
	s_waitcnt vmcnt(36)
	v_lshlrev_b32_e32 v208, 16, v152
	v_and_b32_e32 v209, 0xffff0000, v152
	v_lshlrev_b32_e32 v210, 16, v153
	v_and_b32_e32 v211, 0xffff0000, v153
	v_lshlrev_b32_e32 v212, 16, v154
	v_and_b32_e32 v213, 0xffff0000, v154
	v_lshlrev_b32_e32 v214, 16, v155
	v_and_b32_e32 v215, 0xffff0000, v155
	v_lshlrev_b32_e32 v216, 16, v156
	v_and_b32_e32 v217, 0xffff0000, v156
	v_lshlrev_b32_e32 v218, 16, v157
	v_and_b32_e32 v219, 0xffff0000, v157
	v_lshlrev_b32_e32 v220, 16, v158
	v_and_b32_e32 v221, 0xffff0000, v158
	v_lshlrev_b32_e32 v222, 16, v159
	v_and_b32_e32 v223, 0xffff0000, v159
	v_pk_mul_f32 v[224:225], v[208:209], v[208:209]
	v_pk_fma_f32 v[224:225], v[210:211], v[210:211], v[224:225]
	v_pk_fma_f32 v[224:225], v[212:213], v[212:213], v[224:225]
	v_pk_fma_f32 v[224:225], v[214:215], v[214:215], v[224:225]
	v_pk_fma_f32 v[224:225], v[216:217], v[216:217], v[224:225]
	v_pk_fma_f32 v[224:225], v[218:219], v[218:219], v[224:225]
	v_pk_fma_f32 v[224:225], v[220:221], v[220:221], v[224:225]
	v_pk_fma_f32 v[224:225], v[222:223], v[222:223], v[224:225]
	v_add_f32_e32 v224, v224, v225
	v_lshlrev_b32_e32 v192, 16, v144
	v_and_b32_e32 v193, 0xffff0000, v144
	v_lshlrev_b32_e32 v194, 16, v145
	v_and_b32_e32 v195, 0xffff0000, v145
	v_add_f32_dpp v224, v224, v224 quad_perm:[1,0,3,2] row_mask:0xf bank_mask:0xf bound_ctrl:1
	v_lshlrev_b32_e32 v196, 16, v146
	v_and_b32_e32 v197, 0xffff0000, v146
	v_lshlrev_b32_e32 v198, 16, v147
	v_and_b32_e32 v199, 0xffff0000, v147
	v_add_f32_dpp v224, v224, v224 quad_perm:[2,3,0,1] row_mask:0xf bank_mask:0xf bound_ctrl:1
	v_lshlrev_b32_e32 v200, 16, v148
	v_and_b32_e32 v201, 0xffff0000, v148
	v_lshlrev_b32_e32 v202, 16, v149
	v_and_b32_e32 v203, 0xffff0000, v149
	v_add_f32_dpp v224, v224, v224 row_half_mirror row_mask:0xf bank_mask:0xf bound_ctrl:1
	v_lshlrev_b32_e32 v204, 16, v150
	v_and_b32_e32 v205, 0xffff0000, v150
	v_lshlrev_b32_e32 v206, 16, v151
	v_and_b32_e32 v207, 0xffff0000, v151
	v_add_f32_dpp v224, v224, v224 row_mirror row_mask:0xf bank_mask:0xf bound_ctrl:1
	s_nop 0
	v_readlane_b32 s16, v224, 0
	v_readlane_b32 s17, v224, 16
	v_readlane_b32 s18, v224, 32
	v_readlane_b32 s19, v224, 48
	s_nop 1
	v_mov_b32_e32 v224, s17
	v_add_f32_e32 v224, s16, v224
	v_add_f32_e32 v224, s18, v224
	v_add_f32_e32 v224, s19, v224
	v_fmamk_f32 v224, v224, 0x3a800000, v226
	v_rsq_f32_e32 v224, v224
	s_nop 0
	v_mul_f32_e32 v224, 0.5, v224
	v_pk_mul_f32 v[208:209], v[224:225], v[208:209] op_sel_hi:[0,1]
	v_pk_mul_f32 v[210:211], v[224:225], v[210:211] op_sel_hi:[0,1]
	v_pk_mul_f32 v[212:213], v[224:225], v[212:213] op_sel_hi:[0,1]
	v_pk_mul_f32 v[214:215], v[224:225], v[214:215] op_sel_hi:[0,1]
	v_pk_mul_f32 v[216:217], v[224:225], v[216:217] op_sel_hi:[0,1]
	v_pk_mul_f32 v[218:219], v[224:225], v[218:219] op_sel_hi:[0,1]
	v_pk_mul_f32 v[220:221], v[224:225], v[220:221] op_sel_hi:[0,1]
	v_pk_mul_f32 v[222:223], v[224:225], v[222:223] op_sel_hi:[0,1]
	v_pk_fma_f32 v[192:193], v[0:1], v[208:209], v[192:193]
	v_pk_fma_f32 v[194:195], v[2:3], v[210:211], v[194:195]
	v_pk_fma_f32 v[196:197], v[4:5], v[212:213], v[196:197]
	v_pk_fma_f32 v[198:199], v[6:7], v[214:215], v[198:199]
	v_pk_fma_f32 v[200:201], v[8:9], v[216:217], v[200:201]
	v_pk_fma_f32 v[202:203], v[10:11], v[218:219], v[202:203]
	v_pk_fma_f32 v[204:205], v[12:13], v[220:221], v[204:205]
	v_pk_fma_f32 v[206:207], v[14:15], v[222:223], v[206:207]
	s_add_u32 s20, s20, 0x800000
	s_addc_u32 s21, s21, 0
	global_store_dwordx4 v19, v[192:195], s[20:21] offset:0 nt
	global_store_dwordx4 v19, v[196:199], s[20:21] offset:1024 nt
	global_store_dwordx4 v19, v[200:203], s[20:21] offset:2048 nt
	global_store_dwordx4 v19, v[204:207], s[20:21] offset:3072 nt
	s_waitcnt vmcnt(28)
; __device__ __forceinline__ unsigned cvt_pk_bf16(float lo, float hi) { const f32x2_t v = {lo, hi}; const bf16x2_t b = __builtin_convertvector(v, bf16x2_t); return __builtin_bit_cast(unsigned, b); }
; __device__ __forceinline__ float lo_bf(unsigned x) { return __uint_as_float(x << 16); }
; __device__ __forceinline__ float hi_bf(unsigned x) { return __uint_as_float(x & 0xffff0000u); }
; __device__ __forceinline__ void rows_proc(PR P, const int mode, const int row, const int lane, float4 (&xv)[4], const float4 (&fo)[4], const float4 (&gp)[4], const float4 (&gn)[4]) {
;     ...
;     if (mode != 0) {
;         float ss = 0.f;
; #pragma unroll
;         for (int q = 0; q < 4; ++q) ss += fo[q].x * fo[q].x + fo[q].y * fo[q].y + fo[q].z * fo[q].z + fo[q].w * fo[q].w;
;         ss = wave_sum(ss); const float r = rsqrtf(ss * (1.0f / 1024.0f) + 1e-6f) * (mode == 2 ? 1.0f : 0.5f);
; #pragma unroll
;         for (int q = 0; q < 4; ++q) {
;             xv[q].x += fo[q].x * r * gp[q].x; xv[q].y += fo[q].y * r * gp[q].y; xv[q].z += fo[q].z * r * gp[q].z; xv[q].w += fo[q].w * r * gp[q].w;
;             if (mode == 3) { const f32x4 t_ = {xv[q].x, xv[q].y, xv[q].z, xv[q].w}; __builtin_nontemporal_store(t_, (f32x4*)(P.out + (size_t)row * 1024 + (q * 64 + lane) * 4)); }
;             else { bf16_t* xo = (mode == 1 ? (bf16_t*)P.out : (bf16_t*)(P.ws + WS_FO + 34603008)) + (size_t)row * 1024; u32x2 t; t.x = pg8::cvt_pk_bf16(xv[q].x, xv[q].y); t.y = pg8::cvt_pk_bf16(xv[q].z, xv[q].w);
;                 __builtin_nontemporal_store(t, (u32x2*)(xo + (q * 64 + lane) * 4)); } }
;         if (mode == 3) return;
; __device__ __forceinline__ void rows_phase(PR P, const int mode, LAS float* ldsf, const int wv) {
;     ...
;             for (int q = 0; q < 4; ++q) {
;                 xv[q] = mode <= 1 ? R.xf[q] : make_float4(lo_bf(R.xb[q].x), hi_bf(R.xb[q].x), lo_bf(R.xb[q].y), hi_bf(R.xb[q].y));
;                 fo[q] = make_float4(lo_bf(R.fb[q].x), hi_bf(R.fb[q].x), lo_bf(R.fb[q].y), hi_bf(R.fb[q].y)); }
	v_lshlrev_b32_e32 v208, 16, v72
	v_and_b32_e32 v209, 0xffff0000, v72
	v_lshlrev_b32_e32 v210, 16, v73
	v_and_b32_e32 v211, 0xffff0000, v73
	v_lshlrev_b32_e32 v212, 16, v74
	v_and_b32_e32 v213, 0xffff0000, v74
	v_lshlrev_b32_e32 v214, 16, v75
	v_and_b32_e32 v215, 0xffff0000, v75
	v_lshlrev_b32_e32 v216, 16, v76
	v_and_b32_e32 v217, 0xffff0000, v76
	v_lshlrev_b32_e32 v218, 16, v77
	v_and_b32_e32 v219, 0xffff0000, v77
	v_lshlrev_b32_e32 v220, 16, v78
	v_and_b32_e32 v221, 0xffff0000, v78
	v_lshlrev_b32_e32 v222, 16, v79
	v_and_b32_e32 v223, 0xffff0000, v79
	v_pk_mul_f32 v[224:225], v[208:209], v[208:209]
	v_pk_fma_f32 v[224:225], v[210:211], v[210:211], v[224:225]
	v_pk_fma_f32 v[224:225], v[212:213], v[212:213], v[224:225]
	v_pk_fma_f32 v[224:225], v[214:215], v[214:215], v[224:225]
	v_pk_fma_f32 v[224:225], v[216:217], v[216:217], v[224:225]
	v_pk_fma_f32 v[224:225], v[218:219], v[218:219], v[224:225]
	v_pk_fma_f32 v[224:225], v[220:221], v[220:221], v[224:225]
	v_pk_fma_f32 v[224:225], v[222:223], v[222:223], v[224:225]
	v_add_f32_e32 v224, v224, v225
	v_lshlrev_b32_e32 v192, 16, v64
	v_and_b32_e32 v193, 0xffff0000, v64
	v_lshlrev_b32_e32 v194, 16, v65
	v_and_b32_e32 v195, 0xffff0000, v65
	v_add_f32_dpp v224, v224, v224 quad_perm:[1,0,3,2] row_mask:0xf bank_mask:0xf bound_ctrl:1
	v_lshlrev_b32_e32 v196, 16, v66
	v_and_b32_e32 v197, 0xffff0000, v66
	v_lshlrev_b32_e32 v198, 16, v67
	v_and_b32_e32 v199, 0xffff0000, v67
	v_add_f32_dpp v224, v224, v224 quad_perm:[2,3,0,1] row_mask:0xf bank_mask:0xf bound_ctrl:1
	v_lshlrev_b32_e32 v200, 16, v68
	v_and_b32_e32 v201, 0xffff0000, v68
	v_lshlrev_b32_e32 v202, 16, v69
	v_and_b32_e32 v203, 0xffff0000, v69
	v_add_f32_dpp v224, v224, v224 row_half_mirror row_mask:0xf bank_mask:0xf bound_ctrl:1
	v_lshlrev_b32_e32 v204, 16, v70
	v_and_b32_e32 v205, 0xffff0000, v70
	v_lshlrev_b32_e32 v206, 16, v71
	v_and_b32_e32 v207, 0xffff0000, v71
	v_add_f32_dpp v224, v224, v224 row_mirror row_mask:0xf bank_mask:0xf bound_ctrl:1
	s_nop 0
	v_readlane_b32 s16, v224, 0
	v_readlane_b32 s17, v224, 16
	v_readlane_b32 s18, v224, 32
	v_readlane_b32 s19, v224, 48
	s_nop 1
	v_mov_b32_e32 v224, s17
	v_add_f32_e32 v224, s16, v224
	v_add_f32_e32 v224, s18, v224
	v_add_f32_e32 v224, s19, v224
	v_fmamk_f32 v224, v224, 0x3a800000, v226
	v_rsq_f32_e32 v224, v224
	s_nop 0
	v_mul_f32_e32 v224, 0.5, v224
	v_pk_mul_f32 v[208:209], v[224:225], v[208:209] op_sel_hi:[0,1]
	v_pk_mul_f32 v[210:211], v[224:225], v[210:211] op_sel_hi:[0,1]
	v_pk_mul_f32 v[212:213], v[224:225], v[212:213] op_sel_hi:[0,1]
	v_pk_mul_f32 v[214:215], v[224:225], v[214:215] op_sel_hi:[0,1]
	v_pk_mul_f32 v[216:217], v[224:225], v[216:217] op_sel_hi:[0,1]
	v_pk_mul_f32 v[218:219], v[224:225], v[218:219] op_sel_hi:[0,1]
	v_pk_mul_f32 v[220:221], v[224:225], v[220:221] op_sel_hi:[0,1]
	v_pk_mul_f32 v[222:223], v[224:225], v[222:223] op_sel_hi:[0,1]
	v_pk_fma_f32 v[192:193], v[0:1], v[208:209], v[192:193]
	v_pk_fma_f32 v[194:195], v[2:3], v[210:211], v[194:195]
	v_pk_fma_f32 v[196:197], v[4:5], v[212:213], v[196:197]
	v_pk_fma_f32 v[198:199], v[6:7], v[214:215], v[198:199]
	v_pk_fma_f32 v[200:201], v[8:9], v[216:217], v[200:201]
	v_pk_fma_f32 v[202:203], v[10:11], v[218:219], v[202:203]
	v_pk_fma_f32 v[204:205], v[12:13], v[220:221], v[204:205]
	v_pk_fma_f32 v[206:207], v[14:15], v[222:223], v[206:207]
	s_add_u32 s20, s20, 0x800000
	s_addc_u32 s21, s21, 0
	global_store_dwordx4 v19, v[192:195], s[20:21] offset:0 nt
	global_store_dwordx4 v19, v[196:199], s[20:21] offset:1024 nt
	global_store_dwordx4 v19, v[200:203], s[20:21] offset:2048 nt
	global_store_dwordx4 v19, v[204:207], s[20:21] offset:3072 nt
	s_waitcnt vmcnt(20)
; __device__ __forceinline__ unsigned cvt_pk_bf16(float lo, float hi) { const f32x2_t v = {lo, hi}; const bf16x2_t b = __builtin_convertvector(v, bf16x2_t); return __builtin_bit_cast(unsigned, b); }
; __device__ __forceinline__ float lo_bf(unsigned x) { return __uint_as_float(x << 16); }
; __device__ __forceinline__ float hi_bf(unsigned x) { return __uint_as_float(x & 0xffff0000u); }
; __device__ __forceinline__ void rows_proc(PR P, const int mode, const int row, const int lane, float4 (&xv)[4], const float4 (&fo)[4], const float4 (&gp)[4], const float4 (&gn)[4]) {
;     ...
;     if (mode != 0) {
;         float ss = 0.f;
; #pragma unroll
;         for (int q = 0; q < 4; ++q) ss += fo[q].x * fo[q].x + fo[q].y * fo[q].y + fo[q].z * fo[q].z + fo[q].w * fo[q].w;
;         ss = wave_sum(ss); const float r = rsqrtf(ss * (1.0f / 1024.0f) + 1e-6f) * (mode == 2 ? 1.0f : 0.5f);
; #pragma unroll
;         for (int q = 0; q < 4; ++q) {
;             xv[q].x += fo[q].x * r * gp[q].x; xv[q].y += fo[q].y * r * gp[q].y; xv[q].z += fo[q].z * r * gp[q].z; xv[q].w += fo[q].w * r * gp[q].w;
;             if (mode == 3) { const f32x4 t_ = {xv[q].x, xv[q].y, xv[q].z, xv[q].w}; __builtin_nontemporal_store(t_, (f32x4*)(P.out + (size_t)row * 1024 + (q * 64 + lane) * 4)); }
;             else { bf16_t* xo = (mode == 1 ? (bf16_t*)P.out : (bf16_t*)(P.ws + WS_FO + 34603008)) + (size_t)row * 1024; u32x2 t; t.x = pg8::cvt_pk_bf16(xv[q].x, xv[q].y); t.y = pg8::cvt_pk_bf16(xv[q].z, xv[q].w);
;                 __builtin_nontemporal_store(t, (u32x2*)(xo + (q * 64 + lane) * 4)); } }
;         if (mode == 3) return;
; __device__ __forceinline__ void rows_phase(PR P, const int mode, LAS float* ldsf, const int wv) {
;     ...
;             for (int q = 0; q < 4; ++q) {
;                 xv[q] = mode <= 1 ? R.xf[q] : make_float4(lo_bf(R.xb[q].x), hi_bf(R.xb[q].x), lo_bf(R.xb[q].y), hi_bf(R.xb[q].y));
;                 fo[q] = make_float4(lo_bf(R.fb[q].x), hi_bf(R.fb[q].x), lo_bf(R.fb[q].y), hi_bf(R.fb[q].y)); }
	v_lshlrev_b32_e32 v208, 16, v88
	v_and_b32_e32 v209, 0xffff0000, v88
	v_lshlrev_b32_e32 v210, 16, v89
	v_and_b32_e32 v211, 0xffff0000, v89
	v_lshlrev_b32_e32 v212, 16, v90
	v_and_b32_e32 v213, 0xffff0000, v90
	v_lshlrev_b32_e32 v214, 16, v91
	v_and_b32_e32 v215, 0xffff0000, v91
	v_lshlrev_b32_e32 v216, 16, v92
	v_and_b32_e32 v217, 0xffff0000, v92
	v_lshlrev_b32_e32 v218, 16, v93
	v_and_b32_e32 v219, 0xffff0000, v93
	v_lshlrev_b32_e32 v220, 16, v94
	v_and_b32_e32 v221, 0xffff0000, v94
	v_lshlrev_b32_e32 v222, 16, v95
	v_and_b32_e32 v223, 0xffff0000, v95
	v_pk_mul_f32 v[224:225], v[208:209], v[208:209]
	v_pk_fma_f32 v[224:225], v[210:211], v[210:211], v[224:225]
	v_pk_fma_f32 v[224:225], v[212:213], v[212:213], v[224:225]
	v_pk_fma_f32 v[224:225], v[214:215], v[214:215], v[224:225]
	v_pk_fma_f32 v[224:225], v[216:217], v[216:217], v[224:225]
	v_pk_fma_f32 v[224:225], v[218:219], v[218:219], v[224:225]
	v_pk_fma_f32 v[224:225], v[220:221], v[220:221], v[224:225]
	v_pk_fma_f32 v[224:225], v[222:223], v[222:223], v[224:225]
	v_add_f32_e32 v224, v224, v225
	v_lshlrev_b32_e32 v192, 16, v80
	v_and_b32_e32 v193, 0xffff0000, v80
	v_lshlrev_b32_e32 v194, 16, v81
	v_and_b32_e32 v195, 0xffff0000, v81
	v_add_f32_dpp v224, v224, v224 quad_perm:[1,0,3,2] row_mask:0xf bank_mask:0xf bound_ctrl:1
	v_lshlrev_b32_e32 v196, 16, v82
	v_and_b32_e32 v197, 0xffff0000, v82
	v_lshlrev_b32_e32 v198, 16, v83
	v_and_b32_e32 v199, 0xffff0000, v83
	v_add_f32_dpp v224, v224, v224 quad_perm:[2,3,0,1] row_mask:0xf bank_mask:0xf bound_ctrl:1
	v_lshlrev_b32_e32 v200, 16, v84
	v_and_b32_e32 v201, 0xffff0000, v84
	v_lshlrev_b32_e32 v202, 16, v85
	v_and_b32_e32 v203, 0xffff0000, v85
	v_add_f32_dpp v224, v224, v224 row_half_mirror row_mask:0xf bank_mask:0xf bound_ctrl:1
	v_lshlrev_b32_e32 v204, 16, v86
	v_and_b32_e32 v205, 0xffff0000, v86
	v_lshlrev_b32_e32 v206, 16, v87
	v_and_b32_e32 v207, 0xffff0000, v87
	v_add_f32_dpp v224, v224, v224 row_mirror row_mask:0xf bank_mask:0xf bound_ctrl:1
	s_nop 0
	v_readlane_b32 s16, v224, 0
	v_readlane_b32 s17, v224, 16
	v_readlane_b32 s18, v224, 32
	v_readlane_b32 s19, v224, 48
	s_nop 1
	v_mov_b32_e32 v224, s17
	v_add_f32_e32 v224, s16, v224
	v_add_f32_e32 v224, s18, v224
	v_add_f32_e32 v224, s19, v224
	v_fmamk_f32 v224, v224, 0x3a800000, v226
	v_rsq_f32_e32 v224, v224
	s_nop 0
	v_mul_f32_e32 v224, 0.5, v224
	v_pk_mul_f32 v[208:209], v[224:225], v[208:209] op_sel_hi:[0,1]
	v_pk_mul_f32 v[210:211], v[224:225], v[210:211] op_sel_hi:[0,1]
	v_pk_mul_f32 v[212:213], v[224:225], v[212:213] op_sel_hi:[0,1]
	v_pk_mul_f32 v[214:215], v[224:225], v[214:215] op_sel_hi:[0,1]
	v_pk_mul_f32 v[216:217], v[224:225], v[216:217] op_sel_hi:[0,1]
	v_pk_mul_f32 v[218:219], v[224:225], v[218:219] op_sel_hi:[0,1]
	v_pk_mul_f32 v[220:221], v[224:225], v[220:221] op_sel_hi:[0,1]
	v_pk_mul_f32 v[222:223], v[224:225], v[222:223] op_sel_hi:[0,1]
	v_pk_fma_f32 v[192:193], v[0:1], v[208:209], v[192:193]
	v_pk_fma_f32 v[194:195], v[2:3], v[210:211], v[194:195]
	v_pk_fma_f32 v[196:197], v[4:5], v[212:213], v[196:197]
	v_pk_fma_f32 v[198:199], v[6:7], v[214:215], v[198:199]
	v_pk_fma_f32 v[200:201], v[8:9], v[216:217], v[200:201]
	v_pk_fma_f32 v[202:203], v[10:11], v[218:219], v[202:203]
	v_pk_fma_f32 v[204:205], v[12:13], v[220:221], v[204:205]
	v_pk_fma_f32 v[206:207], v[14:15], v[222:223], v[206:207]
	s_add_u32 s20, s20, 0x800000
	s_addc_u32 s21, s21, 0
	global_store_dwordx4 v19, v[192:195], s[20:21] offset:0 nt
	global_store_dwordx4 v19, v[196:199], s[20:21] offset:1024 nt
	global_store_dwordx4 v19, v[200:203], s[20:21] offset:2048 nt
	global_store_dwordx4 v19, v[204:207], s[20:21] offset:3072 nt
